# row_pass (mode 1 with XN): software-pipelined row loop, two register sets
# baseline (speedup 1.0000x reference)
.LBB0_127:
	v_readlane_b32 s18, v252, 0
	v_readlane_b32 s20, v252, 51
	v_readlane_b32 s19, v252, 1
	v_readlane_b32 s21, v252, 52
	s_mov_b64 s[4:5], s[18:19]
	s_mov_b64 s[30:31], s[18:19]
	v_mov_b32_e32 v0, v162
	s_andn2_b64 vcc, exec, s[20:21]
	s_cbranch_vccnz .LBB0_150
	s_xor_b64 s[20:21], s[6:7], -1
	v_readlane_b32 s29, v251, 62
	s_cmp_lg_u32 s29, 11
	s_cselect_b64 s[34:35], -1, 0
	s_cmp_eq_u32 s29, 8
	s_cselect_b64 s[36:37], -1, 0
	s_and_b64 s[38:39], s[36:37], exec
	s_cselect_b32 s23, 38, 41
	s_cmp_lg_u32 s29, 5
	s_cselect_b32 s23, s23, 33
	s_lshl_b32 s23, s23, 3
	s_load_dwordx2 s[4:5], s[4:5], s23 offset:0x0
	s_nop 0
	s_load_dwordx2 s[40:41], s[30:31], 0x158
	s_xor_b64 s[30:31], s[64:65], -1
	s_or_b64 s[30:31], s[30:31], s[34:35]
	s_and_b64 s[34:35], s[64:65], exec
	s_cselect_b32 s23, 0x1000, 0
	s_waitcnt lgkmcnt(0)
	s_add_u32 s4, s4, s23
	s_load_dwordx4 s[60:63], s[18:19], 0x150
	v_lshlrev_b32_e32 v18, 2, v0
	s_addc_u32 s5, s5, 0
	v_ashrrev_i32_e32 v19, 31, v18
	s_and_b64 s[6:7], s[6:7], s[36:37]
	s_waitcnt vmcnt(0)
	v_lshlrev_b64 v[2:3], 2, v[18:19]
	s_xor_b64 s[34:35], s[6:7], -1
	v_lshl_add_u64 v[20:21], s[4:5], 0, v[2:3]
	s_and_b64 s[4:5], s[64:65], exec
	v_readlane_b32 s5, v251, 26
	s_cselect_b32 s23, 0x80000, 0
	s_cselect_b32 s4, 0x1000000, 0
	s_waitcnt lgkmcnt(0)
	s_add_u32 s36, s62, s5
	v_readlane_b32 s5, v251, 27
	s_addc_u32 s37, s63, s5
	v_readlane_b32 s38, v251, 45
	v_readlane_b32 s39, v251, 46
	s_add_u32 s29, s38, s4
	s_addc_u32 s59, s39, 0
	v_readlane_b32 s4, v251, 51
	v_readlane_b32 s5, v251, 52
	s_add_u32 s38, s62, s4
	s_addc_u32 s39, s63, s5
	s_add_u32 s40, s40, s4
	s_addc_u32 s41, s41, s5
	v_readlane_b32 s4, v251, 30
	v_readlane_b32 s5, v251, 31
	s_add_u32 s4, s60, s4
	s_addc_u32 s5, s61, s5
	v_readlane_b32 s42, v251, 49
	v_lshlrev_b64 v[22:23], 1, v[18:19]
	v_lshl_add_u64 v[24:25], s[4:5], 0, v[2:3]
	v_readlane_b32 s43, v251, 50
	s_or_b64 s[4:5], s[20:21], s[6:7]
	s_and_b64 vcc, exec, s[4:5]
	s_cbranch_vccnz .LBB0_131
	s_and_b64 vcc, exec, s[30:31]
	s_cbranch_vccz .LBB0_131
	s_branch .Lrp_entry

.LBB0_148:
	s_andn2_b64 vcc, exec, s[44:45]
	s_cbranch_vccnz .LBB0_129
	s_load_dwordx2 s[4:5], s[18:19], 0x10
	s_waitcnt lgkmcnt(0)
	s_add_u32 s4, s4, s29
	s_addc_u32 s5, s5, s59
	s_branch .LBB0_129
	s_branch .LBB0_150
.Lrp_entry:
	v_lshl_add_u64 v[2:3], s[40:41], 0, v[22:23]
	v_add_co_u32_e32 v2, vcc, 0x4c00000, v2
	s_nop 1
	v_addc_co_u32_e32 v3, vcc, 0, v3, vcc
	global_load_dwordx2 v[14:15], v[2:3], off offset:512 nt
	global_load_dwordx2 v[16:17], v[2:3], off offset:1024 nt
	global_load_dwordx2 v[46:47], v[2:3], off nt
	global_load_dwordx2 v[48:49], v[2:3], off offset:1536 nt
	s_nop 0
	global_load_dwordx4 v[2:5], v[20:21], off
	global_load_dwordx4 v[6:9], v[20:21], off offset:1024
	global_load_dwordx4 v[10:13], v[24:25], off offset:-3072 nt
	global_load_dwordx4 v[26:29], v[24:25], off offset:-2048 nt
	global_load_dwordx4 v[30:33], v[20:21], off offset:2048
	global_load_dwordx4 v[34:37], v[20:21], off offset:3072
	global_load_dwordx4 v[38:41], v[24:25], off offset:-1024 nt
	global_load_dwordx4 v[42:45], v[24:25], off nt
	v_mov_b32_e32 v130, v24
	v_mov_b32_e32 v131, v25
	v_lshl_add_u64 v[132:133], s[38:39], 0, v[22:23]
	v_readlane_b32 s4, v251, 53
	v_readlane_b32 s5, v251, 54
	s_add_u32 s42, s42, s4
	s_addc_u32 s43, s43, s5
	v_readlane_b32 s4, v251, 43
	v_readlane_b32 s5, v251, 44
	s_add_u32 s36, s36, s4
	s_addc_u32 s37, s37, s5
	v_readlane_b32 s4, v251, 47
	v_readlane_b32 s5, v251, 48
	s_add_u32 s29, s29, s4
	s_addc_u32 s59, s59, s5
	s_add_u32 s38, s38, s56
	s_addc_u32 s39, s39, s57
	s_add_u32 s40, s40, s56
	v_readlane_b32 s4, v251, 55
	s_addc_u32 s41, s41, s57
	v_readlane_b32 s5, v251, 56
	s_cmpk_gt_i32 s42, 0x41ff
	s_cselect_b32 s98, 0, 1
	s_nop 0
	v_lshl_add_u64 v[24:25], v[24:25], 0, s[4:5]
	global_load_dword v129, v[20:21], off
	global_load_dword v129, v[20:21], off
	global_load_dword v129, v[20:21], off
	global_load_dword v129, v[20:21], off
	global_load_dword v129, v[20:21], off
	global_load_dword v129, v[20:21], off
	global_load_dword v129, v[20:21], off
	global_load_dword v129, v[20:21], off
.Lrp_loop:
	s_cmp_eq_u32 s98, 0
	s_cbranch_scc1 .Lrp_tail1
	v_lshl_add_u64 v[66:67], s[40:41], 0, v[22:23]
	v_add_co_u32_e32 v66, vcc, 0x4c00000, v66
	s_nop 1
	v_addc_co_u32_e32 v67, vcc, 0, v67, vcc
	global_load_dwordx2 v[78:79], v[66:67], off offset:512 nt
	global_load_dwordx2 v[80:81], v[66:67], off offset:1024 nt
	global_load_dwordx2 v[110:111], v[66:67], off nt
	global_load_dwordx2 v[112:113], v[66:67], off offset:1536 nt
	s_nop 0
	global_load_dwordx4 v[66:69], v[20:21], off
	global_load_dwordx4 v[70:73], v[20:21], off offset:1024
	global_load_dwordx4 v[74:77], v[24:25], off offset:-3072 nt
	global_load_dwordx4 v[90:93], v[24:25], off offset:-2048 nt
	global_load_dwordx4 v[94:97], v[20:21], off offset:2048
	global_load_dwordx4 v[98:101], v[20:21], off offset:3072
	global_load_dwordx4 v[102:105], v[24:25], off offset:-1024 nt
	global_load_dwordx4 v[106:109], v[24:25], off nt
	v_mov_b32_e32 v134, v24
	v_mov_b32_e32 v135, v25
	v_lshl_add_u64 v[136:137], s[38:39], 0, v[22:23]
	v_readlane_b32 s4, v251, 53
	v_readlane_b32 s5, v251, 54
	s_add_u32 s42, s42, s4
	s_addc_u32 s43, s43, s5
	v_readlane_b32 s4, v251, 43
	v_readlane_b32 s5, v251, 44
	s_add_u32 s36, s36, s4
	s_addc_u32 s37, s37, s5
	v_readlane_b32 s4, v251, 47
	v_readlane_b32 s5, v251, 48
	s_add_u32 s29, s29, s4
	s_addc_u32 s59, s59, s5
	s_add_u32 s38, s38, s56
	s_addc_u32 s39, s39, s57
	s_add_u32 s40, s40, s56
	v_readlane_b32 s4, v251, 55
	s_addc_u32 s41, s41, s57
	v_readlane_b32 s5, v251, 56
	s_cmpk_gt_i32 s42, 0x41ff
	s_cselect_b32 s98, 0, 1
	s_nop 0
	v_lshl_add_u64 v[24:25], v[24:25], 0, s[4:5]
	s_waitcnt vmcnt(31)
	v_and_b32_e32 v53, 0xffff0000, v14
	v_lshlrev_b32_e32 v51, 16, v14
	s_waitcnt vmcnt(29)
	v_and_b32_e32 v52, 0xffff0000, v46
	v_lshlrev_b32_e32 v50, 16, v46
	v_lshlrev_b32_e32 v54, 16, v47
	v_and_b32_e32 v14, 0xffff0000, v47
	s_waitcnt vmcnt(28)
	v_lshlrev_b32_e32 v47, 16, v48
	v_lshlrev_b32_e32 v46, 16, v16
	v_and_b32_e32 v57, 0xffff0000, v48
	v_and_b32_e32 v56, 0xffff0000, v16
	v_lshlrev_b32_e32 v58, 16, v17
	v_and_b32_e32 v48, 0xffff0000, v17
	v_pk_mul_f32 v[16:17], v[52:53], v[52:53]
	v_lshlrev_b32_e32 v55, 16, v15
	v_pk_mul_f32 v[60:61], v[56:57], v[56:57]
	v_pk_fma_f32 v[16:17], v[50:51], v[50:51], v[16:17]
	v_and_b32_e32 v15, 0xffff0000, v15
	v_lshlrev_b32_e32 v59, 16, v49
	v_pk_fma_f32 v[60:61], v[46:47], v[46:47], v[60:61]
	v_pk_fma_f32 v[16:17], v[54:55], v[54:55], v[16:17]
	v_and_b32_e32 v49, 0xffff0000, v49
	v_pk_fma_f32 v[60:61], v[58:59], v[58:59], v[60:61]
	v_pk_fma_f32 v[16:17], v[14:15], v[14:15], v[16:17]
	v_pk_fma_f32 v[60:61], v[48:49], v[48:49], v[60:61]
	v_add_f32_e32 v0, v16, v17
	v_add_f32_e32 v0, v0, v60
	v_add_f32_e32 v0, v0, v61
	ds_bpermute_b32 v16, v163, v0
	v_mov_b32_e32 v61, v14
	v_mov_b32_e32 v60, v54
	v_mov_b32_e32 v62, v58
	v_mov_b32_e32 v63, v48
	s_waitcnt lgkmcnt(0)
	v_add_f32_e32 v0, v0, v16
	ds_bpermute_b32 v16, v164, v0
	v_mov_b32_e32 v48, v59
	s_waitcnt lgkmcnt(0)
	v_add_f32_e32 v0, v0, v16
	ds_bpermute_b32 v16, v165, v0
	s_waitcnt lgkmcnt(0)
	v_add_f32_e32 v0, v0, v16
	ds_bpermute_b32 v17, v166, v0
	v_mov_b32_e32 v16, v50
	s_waitcnt lgkmcnt(0)
	v_add_f32_e32 v0, v0, v17
	ds_bpermute_b32 v50, v167, v0
	v_mov_b32_e32 v17, v52
	v_mov_b32_e32 v52, v51
	v_mov_b32_e32 v51, v56
	v_mov_b32_e32 v56, v47
	s_waitcnt lgkmcnt(0)
	v_add_f32_e32 v0, v0, v50
	ds_bpermute_b32 v14, v168, v0
	v_mov_b32_e32 v50, v46
	s_waitcnt lgkmcnt(0)
	v_add_f32_e32 v0, v0, v14
	v_fmamk_f32 v0, v0, 0x3a800000, v169
	v_mul_f32_e32 v14, 0x4b800000, v0
	v_cmp_gt_f32_e32 vcc, s74, v0
	s_nop 1
	v_cndmask_b32_e32 v0, v0, v14, vcc
	v_rsq_f32_e32 v0, v0
	v_mov_b32_e32 v14, v55
	v_mul_f32_e32 v46, 0x45800000, v0
	v_cndmask_b32_e32 v0, v0, v46, vcc
	v_pk_mul_f32 v[46:47], v[16:17], v[0:1] op_sel_hi:[1,0]
	v_pk_mul_f32 v[16:17], v[60:61], v[0:1] op_sel_hi:[1,0]
	v_pk_mul_f32 v[52:53], v[52:53], v[0:1] op_sel_hi:[1,0]
	v_pk_mul_f32 v[54:55], v[14:15], v[0:1] op_sel_hi:[1,0]
	v_pk_mul_f32 v[50:51], v[50:51], v[0:1] op_sel_hi:[1,0]
	v_pk_mul_f32 v[58:59], v[62:63], v[0:1] op_sel_hi:[1,0]
	v_pk_mul_f32 v[56:57], v[56:57], v[0:1] op_sel_hi:[1,0]
	v_pk_mul_f32 v[48:49], v[48:49], v[0:1] op_sel_hi:[1,0]
	s_waitcnt vmcnt(25)
	v_pk_fma_f32 v[16:17], v[4:5], v[16:17], v[12:13]
	v_pk_fma_f32 v[14:15], v[2:3], v[46:47], v[10:11]
	s_waitcnt vmcnt(24)
	v_pk_fma_f32 v[12:13], v[8:9], v[54:55], v[28:29]
	v_pk_fma_f32 v[10:11], v[6:7], v[52:53], v[26:27]
	s_waitcnt vmcnt(21)
	v_pk_fma_f32 v[8:9], v[32:33], v[58:59], v[40:41]
	v_pk_fma_f32 v[6:7], v[30:31], v[50:51], v[38:39]
	s_waitcnt vmcnt(20)
	v_pk_fma_f32 v[4:5], v[36:37], v[48:49], v[44:45]
	v_pk_fma_f32 v[2:3], v[34:35], v[56:57], v[42:43]
	v_mov_b32_e32 v26, 1.0
	s_waitcnt vmcnt(23)
	v_pk_mul_f32 v[26:27], v[14:15], v[14:15]
	s_waitcnt vmcnt(22)
	v_pk_mul_f32 v[28:29], v[10:11], v[10:11]
	v_pk_mul_f32 v[30:31], v[16:17], v[16:17]
	v_pk_mul_f32 v[32:33], v[12:13], v[12:13]
	v_mov_b32_e32 v34, v31
	v_mov_b32_e32 v35, v33
	v_mov_b32_e32 v31, v32
	v_mov_b32_e32 v32, v26
	v_mov_b32_e32 v33, v28
	v_mov_b32_e32 v28, v27
	v_pk_add_f32 v[26:27], v[32:33], v[28:29]
	s_waitcnt vmcnt(20)
	v_mov_b32_e32 v32, v2
	v_pk_add_f32 v[26:27], v[30:31], v[26:27]
	v_mov_b32_e32 v33, v6
	v_pk_add_f32 v[26:27], v[34:35], v[26:27]
	v_mov_b32_e32 v34, v3
	v_mov_b32_e32 v35, v7
	v_pk_mul_f32 v[34:35], v[34:35], v[34:35]
	v_mov_b32_e32 v30, v4
	v_mov_b32_e32 v31, v8
	v_pk_fma_f32 v[32:33], v[32:33], v[32:33], v[34:35]
	v_mov_b32_e32 v28, v5
	v_mov_b32_e32 v29, v9
	v_pk_fma_f32 v[30:31], v[30:31], v[30:31], v[32:33]
	v_add_f32_e32 v0, v26, v27
	v_pk_fma_f32 v[28:29], v[28:29], v[28:29], v[30:31]
	s_nop 0
	v_add_f32_e32 v0, v29, v0
	v_add_f32_e32 v0, v28, v0
	ds_bpermute_b32 v26, v163, v0
	s_waitcnt lgkmcnt(0)
	v_add_f32_e32 v0, v0, v26
	ds_bpermute_b32 v26, v164, v0
	s_waitcnt lgkmcnt(0)
	v_add_f32_e32 v0, v0, v26
	ds_bpermute_b32 v26, v165, v0
	s_waitcnt lgkmcnt(0)
	v_add_f32_e32 v0, v0, v26
	ds_bpermute_b32 v26, v166, v0
	s_waitcnt lgkmcnt(0)
	v_add_f32_e32 v0, v0, v26
	ds_bpermute_b32 v26, v167, v0
	s_waitcnt lgkmcnt(0)
	v_add_f32_e32 v0, v0, v26
	ds_bpermute_b32 v26, v168, v0
	s_waitcnt lgkmcnt(0)
	v_add_f32_e32 v0, v0, v26
	v_fmamk_f32 v0, v0, 0x3a800000, v169
	v_mul_f32_e32 v26, 0x4b800000, v0
	v_cmp_gt_f32_e32 vcc, s74, v0
	s_nop 1
	v_cndmask_b32_e32 v0, v0, v26, vcc
	v_rsq_f32_e32 v0, v0
	s_nop 0
	v_mul_f32_e32 v26, 0x45800000, v0
	v_cndmask_b32_e32 v26, v0, v26, vcc
	v_mov_b32_e32 v28, v132
	v_mov_b32_e32 v29, v133
	v_mov_b32_e32 v27, v26
	s_waitcnt vmcnt(23)
	global_store_dwordx4 v[130:131], v[14:17], off offset:-3072 nt
	v_mov_b32_e32 v30, v26
	v_mov_b32_e32 v31, v26
	v_pk_mul_f32 v[16:17], v[16:17], v[30:31]
	v_pk_mul_f32 v[14:15], v[14:15], v[26:27]
	s_nop 0
	v_cvt_pk_bf16_f32 v14, v14, v15
	v_cvt_pk_bf16_f32 v15, v16, v17
	v_add_co_u32_e32 v16, vcc, 0x2b00000, v28
	s_nop 1
	v_addc_co_u32_e32 v17, vcc, 0, v29, vcc
	global_store_dwordx2 v[16:17], v[14:15], off
	s_waitcnt vmcnt(24)
	global_store_dwordx4 v[130:131], v[10:13], off offset:-2048 nt
	v_pk_mul_f32 v[14:15], v[12:13], v[30:31]
	v_pk_mul_f32 v[30:31], v[10:11], v[26:27]
	s_nop 0
	v_cvt_pk_bf16_f32 v30, v30, v31
	v_cvt_pk_bf16_f32 v31, v14, v15
	global_store_dwordx2 v[16:17], v[30:31], off offset:512
	s_waitcnt vmcnt(22)
	global_store_dwordx4 v[130:131], v[6:9], off offset:-1024 nt
	v_mov_b32_e32 v10, v26
	v_mov_b32_e32 v11, v26
	v_pk_mul_f32 v[8:9], v[8:9], v[10:11]
	v_pk_mul_f32 v[6:7], v[6:7], v[26:27]
	s_nop 0
	v_cvt_pk_bf16_f32 v6, v6, v7
	v_cvt_pk_bf16_f32 v7, v8, v9
	v_add_co_u32_e32 v8, vcc, 0x2b00000, v28
	s_nop 1
	v_addc_co_u32_e32 v9, vcc, 0, v29, vcc
	global_store_dwordx2 v[8:9], v[6:7], off offset:1024
	s_waitcnt vmcnt(23)
	global_store_dwordx4 v[130:131], v[2:5], off nt
	v_pk_mul_f32 v[6:7], v[4:5], v[10:11]
	v_pk_mul_f32 v[10:11], v[2:3], v[26:27]
	s_nop 0
	v_cvt_pk_bf16_f32 v10, v10, v11
	v_cvt_pk_bf16_f32 v11, v6, v7
	global_store_dwordx2 v[8:9], v[10:11], off offset:1536
	s_cmp_eq_u32 s98, 0
	s_cbranch_scc1 .Lrp_tail2
	v_lshl_add_u64 v[2:3], s[40:41], 0, v[22:23]
	v_add_co_u32_e32 v2, vcc, 0x4c00000, v2
	s_nop 1
	v_addc_co_u32_e32 v3, vcc, 0, v3, vcc
	global_load_dwordx2 v[14:15], v[2:3], off offset:512 nt
	global_load_dwordx2 v[16:17], v[2:3], off offset:1024 nt
	global_load_dwordx2 v[46:47], v[2:3], off nt
	global_load_dwordx2 v[48:49], v[2:3], off offset:1536 nt
	s_nop 0
	global_load_dwordx4 v[2:5], v[20:21], off
	global_load_dwordx4 v[6:9], v[20:21], off offset:1024
	global_load_dwordx4 v[10:13], v[24:25], off offset:-3072 nt
	global_load_dwordx4 v[26:29], v[24:25], off offset:-2048 nt
	global_load_dwordx4 v[30:33], v[20:21], off offset:2048
	global_load_dwordx4 v[34:37], v[20:21], off offset:3072
	global_load_dwordx4 v[38:41], v[24:25], off offset:-1024 nt
	global_load_dwordx4 v[42:45], v[24:25], off nt
	v_mov_b32_e32 v130, v24
	v_mov_b32_e32 v131, v25
	v_lshl_add_u64 v[132:133], s[38:39], 0, v[22:23]
	v_readlane_b32 s4, v251, 53
	v_readlane_b32 s5, v251, 54
	s_add_u32 s42, s42, s4
	s_addc_u32 s43, s43, s5
	v_readlane_b32 s4, v251, 43
	v_readlane_b32 s5, v251, 44
	s_add_u32 s36, s36, s4
	s_addc_u32 s37, s37, s5
	v_readlane_b32 s4, v251, 47
	v_readlane_b32 s5, v251, 48
	s_add_u32 s29, s29, s4
	s_addc_u32 s59, s59, s5
	s_add_u32 s38, s38, s56
	s_addc_u32 s39, s39, s57
	s_add_u32 s40, s40, s56
	v_readlane_b32 s4, v251, 55
	s_addc_u32 s41, s41, s57
	v_readlane_b32 s5, v251, 56
	s_cmpk_gt_i32 s42, 0x41ff
	s_cselect_b32 s98, 0, 1
	s_nop 0
	v_lshl_add_u64 v[24:25], v[24:25], 0, s[4:5]
	s_waitcnt vmcnt(31)
	v_and_b32_e32 v117, 0xffff0000, v78
	v_lshlrev_b32_e32 v115, 16, v78
	s_waitcnt vmcnt(29)
	v_and_b32_e32 v116, 0xffff0000, v110
	v_lshlrev_b32_e32 v114, 16, v110
	v_lshlrev_b32_e32 v118, 16, v111
	v_and_b32_e32 v78, 0xffff0000, v111
	s_waitcnt vmcnt(28)
	v_lshlrev_b32_e32 v111, 16, v112
	v_lshlrev_b32_e32 v110, 16, v80
	v_and_b32_e32 v121, 0xffff0000, v112
	v_and_b32_e32 v120, 0xffff0000, v80
	v_lshlrev_b32_e32 v122, 16, v81
	v_and_b32_e32 v112, 0xffff0000, v81
	v_pk_mul_f32 v[80:81], v[116:117], v[116:117]
	v_lshlrev_b32_e32 v119, 16, v79
	v_pk_mul_f32 v[124:125], v[120:121], v[120:121]
	v_pk_fma_f32 v[80:81], v[114:115], v[114:115], v[80:81]
	v_and_b32_e32 v79, 0xffff0000, v79
	v_lshlrev_b32_e32 v123, 16, v113
	v_pk_fma_f32 v[124:125], v[110:111], v[110:111], v[124:125]
	v_pk_fma_f32 v[80:81], v[118:119], v[118:119], v[80:81]
	v_and_b32_e32 v113, 0xffff0000, v113
	v_pk_fma_f32 v[124:125], v[122:123], v[122:123], v[124:125]
	v_pk_fma_f32 v[80:81], v[78:79], v[78:79], v[80:81]
	v_pk_fma_f32 v[124:125], v[112:113], v[112:113], v[124:125]
	v_add_f32_e32 v64, v80, v81
	v_add_f32_e32 v64, v64, v124
	v_add_f32_e32 v64, v64, v125
	ds_bpermute_b32 v80, v163, v64
	v_mov_b32_e32 v125, v78
	v_mov_b32_e32 v124, v118
	v_mov_b32_e32 v126, v122
	v_mov_b32_e32 v127, v112
	s_waitcnt lgkmcnt(0)
	v_add_f32_e32 v64, v64, v80
	ds_bpermute_b32 v80, v164, v64
	v_mov_b32_e32 v112, v123
	s_waitcnt lgkmcnt(0)
	v_add_f32_e32 v64, v64, v80
	ds_bpermute_b32 v80, v165, v64
	s_waitcnt lgkmcnt(0)
	v_add_f32_e32 v64, v64, v80
	ds_bpermute_b32 v81, v166, v64
	v_mov_b32_e32 v80, v114
	s_waitcnt lgkmcnt(0)
	v_add_f32_e32 v64, v64, v81
	ds_bpermute_b32 v114, v167, v64
	v_mov_b32_e32 v81, v116
	v_mov_b32_e32 v116, v115
	v_mov_b32_e32 v115, v120
	v_mov_b32_e32 v120, v111
	s_waitcnt lgkmcnt(0)
	v_add_f32_e32 v64, v64, v114
	ds_bpermute_b32 v78, v168, v64
	v_mov_b32_e32 v114, v110
	s_waitcnt lgkmcnt(0)
	v_add_f32_e32 v64, v64, v78
	v_fmamk_f32 v64, v64, 0x3a800000, v169
	v_mul_f32_e32 v78, 0x4b800000, v64
	v_cmp_gt_f32_e32 vcc, s74, v64
	s_nop 1
	v_cndmask_b32_e32 v64, v64, v78, vcc
	v_rsq_f32_e32 v64, v64
	v_mov_b32_e32 v78, v119
	v_mul_f32_e32 v110, 0x45800000, v64
	v_cndmask_b32_e32 v64, v64, v110, vcc
	v_pk_mul_f32 v[110:111], v[80:81], v[64:65] op_sel_hi:[1,0]
	v_pk_mul_f32 v[80:81], v[124:125], v[64:65] op_sel_hi:[1,0]
	v_pk_mul_f32 v[116:117], v[116:117], v[64:65] op_sel_hi:[1,0]
	v_pk_mul_f32 v[118:119], v[78:79], v[64:65] op_sel_hi:[1,0]
	v_pk_mul_f32 v[114:115], v[114:115], v[64:65] op_sel_hi:[1,0]
	v_pk_mul_f32 v[122:123], v[126:127], v[64:65] op_sel_hi:[1,0]
	v_pk_mul_f32 v[120:121], v[120:121], v[64:65] op_sel_hi:[1,0]
	v_pk_mul_f32 v[112:113], v[112:113], v[64:65] op_sel_hi:[1,0]
	s_waitcnt vmcnt(25)
	v_pk_fma_f32 v[80:81], v[68:69], v[80:81], v[76:77]
	v_pk_fma_f32 v[78:79], v[66:67], v[110:111], v[74:75]
	s_waitcnt vmcnt(24)
	v_pk_fma_f32 v[76:77], v[72:73], v[118:119], v[92:93]
	v_pk_fma_f32 v[74:75], v[70:71], v[116:117], v[90:91]
	s_waitcnt vmcnt(21)
	v_pk_fma_f32 v[72:73], v[96:97], v[122:123], v[104:105]
	v_pk_fma_f32 v[70:71], v[94:95], v[114:115], v[102:103]
	s_waitcnt vmcnt(20)
	v_pk_fma_f32 v[68:69], v[100:101], v[112:113], v[108:109]
	v_pk_fma_f32 v[66:67], v[98:99], v[120:121], v[106:107]
	v_mov_b32_e32 v90, 1.0
	s_waitcnt vmcnt(23)
	v_pk_mul_f32 v[90:91], v[78:79], v[78:79]
	s_waitcnt vmcnt(22)
	v_pk_mul_f32 v[92:93], v[74:75], v[74:75]
	v_pk_mul_f32 v[94:95], v[80:81], v[80:81]
	v_pk_mul_f32 v[96:97], v[76:77], v[76:77]
	v_mov_b32_e32 v98, v95
	v_mov_b32_e32 v99, v97
	v_mov_b32_e32 v95, v96
	v_mov_b32_e32 v96, v90
	v_mov_b32_e32 v97, v92
	v_mov_b32_e32 v92, v91
	v_pk_add_f32 v[90:91], v[96:97], v[92:93]
	s_waitcnt vmcnt(20)
	v_mov_b32_e32 v96, v66
	v_pk_add_f32 v[90:91], v[94:95], v[90:91]
	v_mov_b32_e32 v97, v70
	v_pk_add_f32 v[90:91], v[98:99], v[90:91]
	v_mov_b32_e32 v98, v67
	v_mov_b32_e32 v99, v71
	v_pk_mul_f32 v[98:99], v[98:99], v[98:99]
	v_mov_b32_e32 v94, v68
	v_mov_b32_e32 v95, v72
	v_pk_fma_f32 v[96:97], v[96:97], v[96:97], v[98:99]
	v_mov_b32_e32 v92, v69
	v_mov_b32_e32 v93, v73
	v_pk_fma_f32 v[94:95], v[94:95], v[94:95], v[96:97]
	v_add_f32_e32 v64, v90, v91
	v_pk_fma_f32 v[92:93], v[92:93], v[92:93], v[94:95]
	s_nop 0
	v_add_f32_e32 v64, v93, v64
	v_add_f32_e32 v64, v92, v64
	ds_bpermute_b32 v90, v163, v64
	s_waitcnt lgkmcnt(0)
	v_add_f32_e32 v64, v64, v90
	ds_bpermute_b32 v90, v164, v64
	s_waitcnt lgkmcnt(0)
	v_add_f32_e32 v64, v64, v90
	ds_bpermute_b32 v90, v165, v64
	s_waitcnt lgkmcnt(0)
	v_add_f32_e32 v64, v64, v90
	ds_bpermute_b32 v90, v166, v64
	s_waitcnt lgkmcnt(0)
	v_add_f32_e32 v64, v64, v90
	ds_bpermute_b32 v90, v167, v64
	s_waitcnt lgkmcnt(0)
	v_add_f32_e32 v64, v64, v90
	ds_bpermute_b32 v90, v168, v64
	s_waitcnt lgkmcnt(0)
	v_add_f32_e32 v64, v64, v90
	v_fmamk_f32 v64, v64, 0x3a800000, v169
	v_mul_f32_e32 v90, 0x4b800000, v64
	v_cmp_gt_f32_e32 vcc, s74, v64
	s_nop 1
	v_cndmask_b32_e32 v64, v64, v90, vcc
	v_rsq_f32_e32 v64, v64
	s_nop 0
	v_mul_f32_e32 v90, 0x45800000, v64
	v_cndmask_b32_e32 v90, v64, v90, vcc
	v_mov_b32_e32 v92, v136
	v_mov_b32_e32 v93, v137
	v_mov_b32_e32 v91, v90
	s_waitcnt vmcnt(23)
	global_store_dwordx4 v[134:135], v[78:81], off offset:-3072 nt
	v_mov_b32_e32 v94, v90
	v_mov_b32_e32 v95, v90
	v_pk_mul_f32 v[80:81], v[80:81], v[94:95]
	v_pk_mul_f32 v[78:79], v[78:79], v[90:91]
	s_nop 0
	v_cvt_pk_bf16_f32 v78, v78, v79
	v_cvt_pk_bf16_f32 v79, v80, v81
	v_add_co_u32_e32 v80, vcc, 0x2b00000, v92
	s_nop 1
	v_addc_co_u32_e32 v81, vcc, 0, v93, vcc
	global_store_dwordx2 v[80:81], v[78:79], off
	s_waitcnt vmcnt(24)
	global_store_dwordx4 v[134:135], v[74:77], off offset:-2048 nt
	v_pk_mul_f32 v[78:79], v[76:77], v[94:95]
	v_pk_mul_f32 v[94:95], v[74:75], v[90:91]
	s_nop 0
	v_cvt_pk_bf16_f32 v94, v94, v95
	v_cvt_pk_bf16_f32 v95, v78, v79
	global_store_dwordx2 v[80:81], v[94:95], off offset:512
	s_waitcnt vmcnt(22)
	global_store_dwordx4 v[134:135], v[70:73], off offset:-1024 nt
	v_mov_b32_e32 v74, v90
	v_mov_b32_e32 v75, v90
	v_pk_mul_f32 v[72:73], v[72:73], v[74:75]
	v_pk_mul_f32 v[70:71], v[70:71], v[90:91]
	s_nop 0
	v_cvt_pk_bf16_f32 v70, v70, v71
	v_cvt_pk_bf16_f32 v71, v72, v73
	v_add_co_u32_e32 v72, vcc, 0x2b00000, v92
	s_nop 1
	v_addc_co_u32_e32 v73, vcc, 0, v93, vcc
	global_store_dwordx2 v[72:73], v[70:71], off offset:1024
	s_waitcnt vmcnt(23)
	global_store_dwordx4 v[134:135], v[66:69], off nt
	v_pk_mul_f32 v[70:71], v[68:69], v[74:75]
	v_pk_mul_f32 v[74:75], v[66:67], v[90:91]
	s_nop 0
	v_cvt_pk_bf16_f32 v74, v74, v75
	v_cvt_pk_bf16_f32 v75, v70, v71
	global_store_dwordx2 v[72:73], v[74:75], off offset:1536
	s_branch .Lrp_loop
.Lrp_tail1:
	s_waitcnt vmcnt(0)
	s_waitcnt vmcnt(11)
	v_and_b32_e32 v53, 0xffff0000, v14
	v_lshlrev_b32_e32 v51, 16, v14
	s_waitcnt vmcnt(9)
	v_and_b32_e32 v52, 0xffff0000, v46
	v_lshlrev_b32_e32 v50, 16, v46
	v_lshlrev_b32_e32 v54, 16, v47
	v_and_b32_e32 v14, 0xffff0000, v47
	s_waitcnt vmcnt(8)
	v_lshlrev_b32_e32 v47, 16, v48
	v_lshlrev_b32_e32 v46, 16, v16
	v_and_b32_e32 v57, 0xffff0000, v48
	v_and_b32_e32 v56, 0xffff0000, v16
	v_lshlrev_b32_e32 v58, 16, v17
	v_and_b32_e32 v48, 0xffff0000, v17
	v_pk_mul_f32 v[16:17], v[52:53], v[52:53]
	v_lshlrev_b32_e32 v55, 16, v15
	v_pk_mul_f32 v[60:61], v[56:57], v[56:57]
	v_pk_fma_f32 v[16:17], v[50:51], v[50:51], v[16:17]
	v_and_b32_e32 v15, 0xffff0000, v15
	v_lshlrev_b32_e32 v59, 16, v49
	v_pk_fma_f32 v[60:61], v[46:47], v[46:47], v[60:61]
	v_pk_fma_f32 v[16:17], v[54:55], v[54:55], v[16:17]
	v_and_b32_e32 v49, 0xffff0000, v49
	v_pk_fma_f32 v[60:61], v[58:59], v[58:59], v[60:61]
	v_pk_fma_f32 v[16:17], v[14:15], v[14:15], v[16:17]
	v_pk_fma_f32 v[60:61], v[48:49], v[48:49], v[60:61]
	v_add_f32_e32 v0, v16, v17
	v_add_f32_e32 v0, v0, v60
	v_add_f32_e32 v0, v0, v61
	ds_bpermute_b32 v16, v163, v0
	v_mov_b32_e32 v61, v14
	v_mov_b32_e32 v60, v54
	v_mov_b32_e32 v62, v58
	v_mov_b32_e32 v63, v48
	s_waitcnt lgkmcnt(0)
	v_add_f32_e32 v0, v0, v16
	ds_bpermute_b32 v16, v164, v0
	v_mov_b32_e32 v48, v59
	s_waitcnt lgkmcnt(0)
	v_add_f32_e32 v0, v0, v16
	ds_bpermute_b32 v16, v165, v0
	s_waitcnt lgkmcnt(0)
	v_add_f32_e32 v0, v0, v16
	ds_bpermute_b32 v17, v166, v0
	v_mov_b32_e32 v16, v50
	s_waitcnt lgkmcnt(0)
	v_add_f32_e32 v0, v0, v17
	ds_bpermute_b32 v50, v167, v0
	v_mov_b32_e32 v17, v52
	v_mov_b32_e32 v52, v51
	v_mov_b32_e32 v51, v56
	v_mov_b32_e32 v56, v47
	s_waitcnt lgkmcnt(0)
	v_add_f32_e32 v0, v0, v50
	ds_bpermute_b32 v14, v168, v0
	v_mov_b32_e32 v50, v46
	s_waitcnt lgkmcnt(0)
	v_add_f32_e32 v0, v0, v14
	v_fmamk_f32 v0, v0, 0x3a800000, v169
	v_mul_f32_e32 v14, 0x4b800000, v0
	v_cmp_gt_f32_e32 vcc, s74, v0
	s_nop 1
	v_cndmask_b32_e32 v0, v0, v14, vcc
	v_rsq_f32_e32 v0, v0
	v_mov_b32_e32 v14, v55
	v_mul_f32_e32 v46, 0x45800000, v0
	v_cndmask_b32_e32 v0, v0, v46, vcc
	v_pk_mul_f32 v[46:47], v[16:17], v[0:1] op_sel_hi:[1,0]
	v_pk_mul_f32 v[16:17], v[60:61], v[0:1] op_sel_hi:[1,0]
	v_pk_mul_f32 v[52:53], v[52:53], v[0:1] op_sel_hi:[1,0]
	v_pk_mul_f32 v[54:55], v[14:15], v[0:1] op_sel_hi:[1,0]
	v_pk_mul_f32 v[50:51], v[50:51], v[0:1] op_sel_hi:[1,0]
	v_pk_mul_f32 v[58:59], v[62:63], v[0:1] op_sel_hi:[1,0]
	v_pk_mul_f32 v[56:57], v[56:57], v[0:1] op_sel_hi:[1,0]
	v_pk_mul_f32 v[48:49], v[48:49], v[0:1] op_sel_hi:[1,0]
	s_waitcnt vmcnt(5)
	v_pk_fma_f32 v[16:17], v[4:5], v[16:17], v[12:13]
	v_pk_fma_f32 v[14:15], v[2:3], v[46:47], v[10:11]
	s_waitcnt vmcnt(4)
	v_pk_fma_f32 v[12:13], v[8:9], v[54:55], v[28:29]
	v_pk_fma_f32 v[10:11], v[6:7], v[52:53], v[26:27]
	s_waitcnt vmcnt(1)
	v_pk_fma_f32 v[8:9], v[32:33], v[58:59], v[40:41]
	v_pk_fma_f32 v[6:7], v[30:31], v[50:51], v[38:39]
	s_waitcnt vmcnt(0)
	v_pk_fma_f32 v[4:5], v[36:37], v[48:49], v[44:45]
	v_pk_fma_f32 v[2:3], v[34:35], v[56:57], v[42:43]
	v_mov_b32_e32 v26, 1.0
	s_waitcnt vmcnt(3)
	v_pk_mul_f32 v[26:27], v[14:15], v[14:15]
	s_waitcnt vmcnt(2)
	v_pk_mul_f32 v[28:29], v[10:11], v[10:11]
	v_pk_mul_f32 v[30:31], v[16:17], v[16:17]
	v_pk_mul_f32 v[32:33], v[12:13], v[12:13]
	v_mov_b32_e32 v34, v31
	v_mov_b32_e32 v35, v33
	v_mov_b32_e32 v31, v32
	v_mov_b32_e32 v32, v26
	v_mov_b32_e32 v33, v28
	v_mov_b32_e32 v28, v27
	v_pk_add_f32 v[26:27], v[32:33], v[28:29]
	s_waitcnt vmcnt(0)
	v_mov_b32_e32 v32, v2
	v_pk_add_f32 v[26:27], v[30:31], v[26:27]
	v_mov_b32_e32 v33, v6
	v_pk_add_f32 v[26:27], v[34:35], v[26:27]
	v_mov_b32_e32 v34, v3
	v_mov_b32_e32 v35, v7
	v_pk_mul_f32 v[34:35], v[34:35], v[34:35]
	v_mov_b32_e32 v30, v4
	v_mov_b32_e32 v31, v8
	v_pk_fma_f32 v[32:33], v[32:33], v[32:33], v[34:35]
	v_mov_b32_e32 v28, v5
	v_mov_b32_e32 v29, v9
	v_pk_fma_f32 v[30:31], v[30:31], v[30:31], v[32:33]
	v_add_f32_e32 v0, v26, v27
	v_pk_fma_f32 v[28:29], v[28:29], v[28:29], v[30:31]
	s_nop 0
	v_add_f32_e32 v0, v29, v0
	v_add_f32_e32 v0, v28, v0
	ds_bpermute_b32 v26, v163, v0
	s_waitcnt lgkmcnt(0)
	v_add_f32_e32 v0, v0, v26
	ds_bpermute_b32 v26, v164, v0
	s_waitcnt lgkmcnt(0)
	v_add_f32_e32 v0, v0, v26
	ds_bpermute_b32 v26, v165, v0
	s_waitcnt lgkmcnt(0)
	v_add_f32_e32 v0, v0, v26
	ds_bpermute_b32 v26, v166, v0
	s_waitcnt lgkmcnt(0)
	v_add_f32_e32 v0, v0, v26
	ds_bpermute_b32 v26, v167, v0
	s_waitcnt lgkmcnt(0)
	v_add_f32_e32 v0, v0, v26
	ds_bpermute_b32 v26, v168, v0
	s_waitcnt lgkmcnt(0)
	v_add_f32_e32 v0, v0, v26
	v_fmamk_f32 v0, v0, 0x3a800000, v169
	v_mul_f32_e32 v26, 0x4b800000, v0
	v_cmp_gt_f32_e32 vcc, s74, v0
	s_nop 1
	v_cndmask_b32_e32 v0, v0, v26, vcc
	v_rsq_f32_e32 v0, v0
	s_nop 0
	v_mul_f32_e32 v26, 0x45800000, v0
	v_cndmask_b32_e32 v26, v0, v26, vcc
	v_mov_b32_e32 v28, v132
	v_mov_b32_e32 v29, v133
	v_mov_b32_e32 v27, v26
	s_waitcnt vmcnt(3)
	global_store_dwordx4 v[130:131], v[14:17], off offset:-3072 nt
	v_mov_b32_e32 v30, v26
	v_mov_b32_e32 v31, v26
	v_pk_mul_f32 v[16:17], v[16:17], v[30:31]
	v_pk_mul_f32 v[14:15], v[14:15], v[26:27]
	s_nop 0
	v_cvt_pk_bf16_f32 v14, v14, v15
	v_cvt_pk_bf16_f32 v15, v16, v17
	v_add_co_u32_e32 v16, vcc, 0x2b00000, v28
	s_nop 1
	v_addc_co_u32_e32 v17, vcc, 0, v29, vcc
	global_store_dwordx2 v[16:17], v[14:15], off
	s_waitcnt vmcnt(4)
	global_store_dwordx4 v[130:131], v[10:13], off offset:-2048 nt
	v_pk_mul_f32 v[14:15], v[12:13], v[30:31]
	v_pk_mul_f32 v[30:31], v[10:11], v[26:27]
	s_nop 0
	v_cvt_pk_bf16_f32 v30, v30, v31
	v_cvt_pk_bf16_f32 v31, v14, v15
	global_store_dwordx2 v[16:17], v[30:31], off offset:512
	s_waitcnt vmcnt(2)
	global_store_dwordx4 v[130:131], v[6:9], off offset:-1024 nt
	v_mov_b32_e32 v10, v26
	v_mov_b32_e32 v11, v26
	v_pk_mul_f32 v[8:9], v[8:9], v[10:11]
	v_pk_mul_f32 v[6:7], v[6:7], v[26:27]
	s_nop 0
	v_cvt_pk_bf16_f32 v6, v6, v7
	v_cvt_pk_bf16_f32 v7, v8, v9
	v_add_co_u32_e32 v8, vcc, 0x2b00000, v28
	s_nop 1
	v_addc_co_u32_e32 v9, vcc, 0, v29, vcc
	global_store_dwordx2 v[8:9], v[6:7], off offset:1024
	s_waitcnt vmcnt(3)
	global_store_dwordx4 v[130:131], v[2:5], off nt
	v_pk_mul_f32 v[6:7], v[4:5], v[10:11]
	v_pk_mul_f32 v[10:11], v[2:3], v[26:27]
	s_nop 0
	v_cvt_pk_bf16_f32 v10, v10, v11
	v_cvt_pk_bf16_f32 v11, v6, v7
	global_store_dwordx2 v[8:9], v[10:11], off offset:1536
	s_branch .LBB0_150
.Lrp_tail2:
	s_waitcnt vmcnt(0)
	s_waitcnt vmcnt(11)
	v_and_b32_e32 v117, 0xffff0000, v78
	v_lshlrev_b32_e32 v115, 16, v78
	s_waitcnt vmcnt(9)
	v_and_b32_e32 v116, 0xffff0000, v110
	v_lshlrev_b32_e32 v114, 16, v110
	v_lshlrev_b32_e32 v118, 16, v111
	v_and_b32_e32 v78, 0xffff0000, v111
	s_waitcnt vmcnt(8)
	v_lshlrev_b32_e32 v111, 16, v112
	v_lshlrev_b32_e32 v110, 16, v80
	v_and_b32_e32 v121, 0xffff0000, v112
	v_and_b32_e32 v120, 0xffff0000, v80
	v_lshlrev_b32_e32 v122, 16, v81
	v_and_b32_e32 v112, 0xffff0000, v81
	v_pk_mul_f32 v[80:81], v[116:117], v[116:117]
	v_lshlrev_b32_e32 v119, 16, v79
	v_pk_mul_f32 v[124:125], v[120:121], v[120:121]
	v_pk_fma_f32 v[80:81], v[114:115], v[114:115], v[80:81]
	v_and_b32_e32 v79, 0xffff0000, v79
	v_lshlrev_b32_e32 v123, 16, v113
	v_pk_fma_f32 v[124:125], v[110:111], v[110:111], v[124:125]
	v_pk_fma_f32 v[80:81], v[118:119], v[118:119], v[80:81]
	v_and_b32_e32 v113, 0xffff0000, v113
	v_pk_fma_f32 v[124:125], v[122:123], v[122:123], v[124:125]
	v_pk_fma_f32 v[80:81], v[78:79], v[78:79], v[80:81]
	v_pk_fma_f32 v[124:125], v[112:113], v[112:113], v[124:125]
	v_add_f32_e32 v64, v80, v81
	v_add_f32_e32 v64, v64, v124
	v_add_f32_e32 v64, v64, v125
	ds_bpermute_b32 v80, v163, v64
	v_mov_b32_e32 v125, v78
	v_mov_b32_e32 v124, v118
	v_mov_b32_e32 v126, v122
	v_mov_b32_e32 v127, v112
	s_waitcnt lgkmcnt(0)
	v_add_f32_e32 v64, v64, v80
	ds_bpermute_b32 v80, v164, v64
	v_mov_b32_e32 v112, v123
	s_waitcnt lgkmcnt(0)
	v_add_f32_e32 v64, v64, v80
	ds_bpermute_b32 v80, v165, v64
	s_waitcnt lgkmcnt(0)
	v_add_f32_e32 v64, v64, v80
	ds_bpermute_b32 v81, v166, v64
	v_mov_b32_e32 v80, v114
	s_waitcnt lgkmcnt(0)
	v_add_f32_e32 v64, v64, v81
	ds_bpermute_b32 v114, v167, v64
	v_mov_b32_e32 v81, v116
	v_mov_b32_e32 v116, v115
	v_mov_b32_e32 v115, v120
	v_mov_b32_e32 v120, v111
	s_waitcnt lgkmcnt(0)
	v_add_f32_e32 v64, v64, v114
	ds_bpermute_b32 v78, v168, v64
	v_mov_b32_e32 v114, v110
	s_waitcnt lgkmcnt(0)
	v_add_f32_e32 v64, v64, v78
	v_fmamk_f32 v64, v64, 0x3a800000, v169
	v_mul_f32_e32 v78, 0x4b800000, v64
	v_cmp_gt_f32_e32 vcc, s74, v64
	s_nop 1
	v_cndmask_b32_e32 v64, v64, v78, vcc
	v_rsq_f32_e32 v64, v64
	v_mov_b32_e32 v78, v119
	v_mul_f32_e32 v110, 0x45800000, v64
	v_cndmask_b32_e32 v64, v64, v110, vcc
	v_pk_mul_f32 v[110:111], v[80:81], v[64:65] op_sel_hi:[1,0]
	v_pk_mul_f32 v[80:81], v[124:125], v[64:65] op_sel_hi:[1,0]
	v_pk_mul_f32 v[116:117], v[116:117], v[64:65] op_sel_hi:[1,0]
	v_pk_mul_f32 v[118:119], v[78:79], v[64:65] op_sel_hi:[1,0]
	v_pk_mul_f32 v[114:115], v[114:115], v[64:65] op_sel_hi:[1,0]
	v_pk_mul_f32 v[122:123], v[126:127], v[64:65] op_sel_hi:[1,0]
	v_pk_mul_f32 v[120:121], v[120:121], v[64:65] op_sel_hi:[1,0]
	v_pk_mul_f32 v[112:113], v[112:113], v[64:65] op_sel_hi:[1,0]
	s_waitcnt vmcnt(5)
	v_pk_fma_f32 v[80:81], v[68:69], v[80:81], v[76:77]
	v_pk_fma_f32 v[78:79], v[66:67], v[110:111], v[74:75]
	s_waitcnt vmcnt(4)
	v_pk_fma_f32 v[76:77], v[72:73], v[118:119], v[92:93]
	v_pk_fma_f32 v[74:75], v[70:71], v[116:117], v[90:91]
	s_waitcnt vmcnt(1)
	v_pk_fma_f32 v[72:73], v[96:97], v[122:123], v[104:105]
	v_pk_fma_f32 v[70:71], v[94:95], v[114:115], v[102:103]
	s_waitcnt vmcnt(0)
	v_pk_fma_f32 v[68:69], v[100:101], v[112:113], v[108:109]
	v_pk_fma_f32 v[66:67], v[98:99], v[120:121], v[106:107]
	v_mov_b32_e32 v90, 1.0
	s_waitcnt vmcnt(3)
	v_pk_mul_f32 v[90:91], v[78:79], v[78:79]
	s_waitcnt vmcnt(2)
	v_pk_mul_f32 v[92:93], v[74:75], v[74:75]
	v_pk_mul_f32 v[94:95], v[80:81], v[80:81]
	v_pk_mul_f32 v[96:97], v[76:77], v[76:77]
	v_mov_b32_e32 v98, v95
	v_mov_b32_e32 v99, v97
	v_mov_b32_e32 v95, v96
	v_mov_b32_e32 v96, v90
	v_mov_b32_e32 v97, v92
	v_mov_b32_e32 v92, v91
	v_pk_add_f32 v[90:91], v[96:97], v[92:93]
	s_waitcnt vmcnt(0)
	v_mov_b32_e32 v96, v66
	v_pk_add_f32 v[90:91], v[94:95], v[90:91]
	v_mov_b32_e32 v97, v70
	v_pk_add_f32 v[90:91], v[98:99], v[90:91]
	v_mov_b32_e32 v98, v67
	v_mov_b32_e32 v99, v71
	v_pk_mul_f32 v[98:99], v[98:99], v[98:99]
	v_mov_b32_e32 v94, v68
	v_mov_b32_e32 v95, v72
	v_pk_fma_f32 v[96:97], v[96:97], v[96:97], v[98:99]
	v_mov_b32_e32 v92, v69
	v_mov_b32_e32 v93, v73
	v_pk_fma_f32 v[94:95], v[94:95], v[94:95], v[96:97]
	v_add_f32_e32 v64, v90, v91
	v_pk_fma_f32 v[92:93], v[92:93], v[92:93], v[94:95]
	s_nop 0
	v_add_f32_e32 v64, v93, v64
	v_add_f32_e32 v64, v92, v64
	ds_bpermute_b32 v90, v163, v64
	s_waitcnt lgkmcnt(0)
	v_add_f32_e32 v64, v64, v90
	ds_bpermute_b32 v90, v164, v64
	s_waitcnt lgkmcnt(0)
	v_add_f32_e32 v64, v64, v90
	ds_bpermute_b32 v90, v165, v64
	s_waitcnt lgkmcnt(0)
	v_add_f32_e32 v64, v64, v90
	ds_bpermute_b32 v90, v166, v64
	s_waitcnt lgkmcnt(0)
	v_add_f32_e32 v64, v64, v90
	ds_bpermute_b32 v90, v167, v64
	s_waitcnt lgkmcnt(0)
	v_add_f32_e32 v64, v64, v90
	ds_bpermute_b32 v90, v168, v64
	s_waitcnt lgkmcnt(0)
	v_add_f32_e32 v64, v64, v90
	v_fmamk_f32 v64, v64, 0x3a800000, v169
	v_mul_f32_e32 v90, 0x4b800000, v64
	v_cmp_gt_f32_e32 vcc, s74, v64
	s_nop 1
	v_cndmask_b32_e32 v64, v64, v90, vcc
	v_rsq_f32_e32 v64, v64
	s_nop 0
	v_mul_f32_e32 v90, 0x45800000, v64
	v_cndmask_b32_e32 v90, v64, v90, vcc
	v_mov_b32_e32 v92, v136
	v_mov_b32_e32 v93, v137
	v_mov_b32_e32 v91, v90
	s_waitcnt vmcnt(3)
	global_store_dwordx4 v[134:135], v[78:81], off offset:-3072 nt
	v_mov_b32_e32 v94, v90
	v_mov_b32_e32 v95, v90
	v_pk_mul_f32 v[80:81], v[80:81], v[94:95]
	v_pk_mul_f32 v[78:79], v[78:79], v[90:91]
	s_nop 0
	v_cvt_pk_bf16_f32 v78, v78, v79
	v_cvt_pk_bf16_f32 v79, v80, v81
	v_add_co_u32_e32 v80, vcc, 0x2b00000, v92
	s_nop 1
	v_addc_co_u32_e32 v81, vcc, 0, v93, vcc
	global_store_dwordx2 v[80:81], v[78:79], off
	s_waitcnt vmcnt(4)
	global_store_dwordx4 v[134:135], v[74:77], off offset:-2048 nt
	v_pk_mul_f32 v[78:79], v[76:77], v[94:95]
	v_pk_mul_f32 v[94:95], v[74:75], v[90:91]
	s_nop 0
	v_cvt_pk_bf16_f32 v94, v94, v95
	v_cvt_pk_bf16_f32 v95, v78, v79
	global_store_dwordx2 v[80:81], v[94:95], off offset:512
	s_waitcnt vmcnt(2)
	global_store_dwordx4 v[134:135], v[70:73], off offset:-1024 nt
	v_mov_b32_e32 v74, v90
	v_mov_b32_e32 v75, v90
	v_pk_mul_f32 v[72:73], v[72:73], v[74:75]
	v_pk_mul_f32 v[70:71], v[70:71], v[90:91]
	s_nop 0
	v_cvt_pk_bf16_f32 v70, v70, v71
	v_cvt_pk_bf16_f32 v71, v72, v73
	v_add_co_u32_e32 v72, vcc, 0x2b00000, v92
	s_nop 1
	v_addc_co_u32_e32 v73, vcc, 0, v93, vcc
	global_store_dwordx2 v[72:73], v[70:71], off offset:1024
	s_waitcnt vmcnt(3)
	global_store_dwordx4 v[134:135], v[66:69], off nt
	v_pk_mul_f32 v[70:71], v[68:69], v[74:75]
	v_pk_mul_f32 v[74:75], v[66:67], v[90:91]
	s_nop 0
	v_cvt_pk_bf16_f32 v74, v74, v75
	v_cvt_pk_bf16_f32 v75, v70, v71
	global_store_dwordx2 v[72:73], v[74:75], off offset:1536
